# P3 out-proj epilogue: residual (z0) loads of batches 1-3 issued at epilogue start into dead fragment VGPRs instead of one exposed round trip per batch
# baseline (speedup 1.0000x reference)
.LBB0_777:
	v_lshl_add_u32 v152, s26, 8, v160
	v_lshl_or_b32 v128, s28, 8, v162
	v_ashrrev_i32_e32 v153, 31, v152
	v_ashrrev_i32_e32 v129, 31, v128
	v_lshlrev_b64 v[130:131], 11, v[152:153]
	v_lshl_add_u64 v[130:131], s[74:75], 0, v[130:131]
	v_lshlrev_b64 v[154:155], 1, v[128:129]
	v_lshl_add_u64 v[176:177], v[130:131], 0, v[154:155]
	v_add_u32_e32 v224, 0x20, v152
	v_ashrrev_i32_e32 v225, 31, v224
	v_lshlrev_b64 v[224:225], 11, v[224:225]
	v_lshl_add_u64 v[224:225], s[74:75], 0, v[224:225]
	v_lshl_add_u64 v[224:225], v[224:225], 0, v[154:155]
	global_load_dwordx4 v[192:195], v[224:225], off
	global_load_dwordx4 v[196:199], v[224:225], off offset:256
	v_add_u32_e32 v226, 0x30, v152
	v_ashrrev_i32_e32 v227, 31, v226
	v_lshlrev_b64 v[226:227], 11, v[226:227]
	v_lshl_add_u64 v[226:227], s[74:75], 0, v[226:227]
	v_lshl_add_u64 v[226:227], v[226:227], 0, v[154:155]
	global_load_dwordx4 v[200:203], v[226:227], off
	global_load_dwordx4 v[204:207], v[226:227], off offset:256
	v_add_u32_e32 v224, 0x80, v152
	v_ashrrev_i32_e32 v225, 31, v224
	v_lshlrev_b64 v[224:225], 11, v[224:225]
	v_lshl_add_u64 v[224:225], s[74:75], 0, v[224:225]
	v_lshl_add_u64 v[224:225], v[224:225], 0, v[154:155]
	global_load_dwordx4 v[208:211], v[224:225], off
	global_load_dwordx4 v[212:215], v[224:225], off offset:256
	v_add_u32_e32 v226, 0x90, v152
	v_ashrrev_i32_e32 v227, 31, v226
	v_lshlrev_b64 v[226:227], 11, v[226:227]
	v_lshl_add_u64 v[226:227], s[74:75], 0, v[226:227]
	v_lshl_add_u64 v[226:227], v[226:227], 0, v[154:155]
	global_load_dwordx4 v[216:219], v[226:227], off
	global_load_dwordx4 v[220:223], v[226:227], off offset:256
	global_load_dwordx4 v[168:171], v[176:177], off
	global_load_dwordx4 v[172:175], v[176:177], off offset:256
	v_and_b32_e32 v129, 64, v166
	v_xor_b32_e32 v128, 16, v166
	v_or_b32_e32 v156, 16, v152
	v_add_u32_e32 v129, 64, v129
	v_xor_b32_e32 v130, 32, v166
	v_ashrrev_i32_e32 v157, 31, v156
	v_cmp_lt_i32_e32 vcc, v128, v129
	s_waitcnt vmcnt(0)
	v_lshlrev_b32_e32 v182, 16, v168
	v_cndmask_b32_e32 v131, v166, v128, vcc
	v_cmp_lt_i32_e32 vcc, v130, v129
	v_lshlrev_b64 v[128:129], 11, v[156:157]
	v_lshl_add_u64 v[128:129], s[74:75], 0, v[128:129]
	v_lshl_add_u64 v[158:159], v[128:129], 0, v[154:155]
	v_cndmask_b32_e32 v190, v166, v130, vcc
	v_lshlrev_b32_e32 v167, 2, v131
	global_load_dwordx4 v[132:135], v[158:159], off
	global_load_dwordx4 v[128:131], v[158:159], off offset:256
	v_and_b32_e32 v183, 0xffff0000, v168
	v_lshlrev_b32_e32 v168, 16, v169
	v_and_b32_e32 v169, 0xffff0000, v169
	v_lshlrev_b32_e32 v184, 16, v170
	v_and_b32_e32 v185, 0xffff0000, v170
	v_lshlrev_b32_e32 v170, 16, v171
	v_and_b32_e32 v171, 0xffff0000, v171
	v_lshlrev_b32_e32 v186, 16, v172
	v_and_b32_e32 v187, 0xffff0000, v172
	v_lshlrev_b32_e32 v172, 16, v173
	v_and_b32_e32 v173, 0xffff0000, v173
	v_lshlrev_b32_e32 v188, 16, v174
	v_and_b32_e32 v189, 0xffff0000, v174
	v_lshlrev_b32_e32 v174, 16, v175
	v_and_b32_e32 v175, 0xffff0000, v175
	v_pk_fma_f32 v[126:127], v[168:169], s[16:17], v[126:127] op_sel_hi:[1,0,1]
	v_pk_fma_f32 v[124:125], v[182:183], s[16:17], v[124:125] op_sel_hi:[1,0,1]
	v_pk_fma_f32 v[122:123], v[170:171], s[16:17], v[122:123] op_sel_hi:[1,0,1]
	v_pk_fma_f32 v[120:121], v[184:185], s[16:17], v[120:121] op_sel_hi:[1,0,1]
	v_pk_fma_f32 v[168:169], v[172:173], s[16:17], v[118:119] op_sel_hi:[1,0,1]
	v_pk_fma_f32 v[116:117], v[186:187], s[16:17], v[116:117] op_sel_hi:[1,0,1]
	v_pk_fma_f32 v[170:171], v[174:175], s[16:17], v[114:115] op_sel_hi:[1,0,1]
	v_pk_fma_f32 v[172:173], v[188:189], s[16:17], v[112:113] op_sel_hi:[1,0,1]
	v_cvt_pk_bf16_f32 v112, v124, v125
	v_cvt_pk_bf16_f32 v113, v126, v127
	v_cvt_pk_bf16_f32 v114, v120, v121
	v_cvt_pk_bf16_f32 v115, v122, v123
	v_add_f32_e32 v118, v124, v125
	v_add_f32_e32 v119, v126, v127
	v_add_f32_e32 v174, v120, v121
	v_add_f32_e32 v175, v122, v123
	v_mul_f32_e32 v125, v125, v125
	v_mul_f32_e32 v127, v127, v127
	v_mul_f32_e32 v121, v121, v121
	v_mul_f32_e32 v123, v123, v123
	v_add_f32_e32 v182, v116, v117
	v_add_f32_e32 v183, v168, v169
	v_add_f32_e32 v184, v172, v173
	v_add_f32_e32 v185, v170, v171
	v_mul_f32_e32 v186, v117, v117
	v_mul_f32_e32 v187, v169, v169
	v_mul_f32_e32 v188, v173, v173
	v_mul_f32_e32 v189, v171, v171
	global_store_dwordx4 v[176:177], v[112:115], off
	v_fmac_f32_e32 v125, v124, v124
	v_fmac_f32_e32 v127, v126, v126
	v_add_f32_e32 v112, v118, v119
	v_add_f32_e32 v113, v174, v175
	v_fmac_f32_e32 v121, v120, v120
	v_fmac_f32_e32 v123, v122, v122
	v_add_f32_e32 v114, v182, v183
	v_add_f32_e32 v115, v184, v185
	v_fmac_f32_e32 v186, v116, v116
	v_fmac_f32_e32 v187, v168, v168
	v_fmac_f32_e32 v188, v172, v172
	v_fmac_f32_e32 v189, v170, v170
	v_add_f32_e32 v112, v112, v113
	v_add_f32_e32 v113, v125, v127
	v_add_f32_e32 v118, v121, v123
	v_add_f32_e32 v114, v114, v115
	v_add_f32_e32 v115, v186, v187
	v_add_f32_e32 v119, v188, v189
	v_add_f32_e32 v112, 0, v112
	v_add_f32_e32 v113, v113, v118
	v_add_f32_e32 v115, v115, v119
	v_add_f32_e32 v112, v112, v114
	v_add_f32_e32 v115, v113, v115
	ds_bpermute_b32 v114, v167, v112
	ds_bpermute_b32 v119, v167, v115
	v_cvt_pk_bf16_f32 v118, v116, v117
	s_waitcnt lgkmcnt(1)
	v_add_f32_e32 v113, v112, v114
	v_lshlrev_b32_e32 v112, 2, v190
	s_waitcnt lgkmcnt(0)
	v_add_f32_e32 v115, v115, v119
	ds_bpermute_b32 v114, v112, v113
	ds_bpermute_b32 v116, v112, v115
	v_cvt_pk_bf16_f32 v119, v168, v169
	v_cvt_pk_bf16_f32 v120, v172, v173
	v_cvt_pk_bf16_f32 v121, v170, v171
	global_store_dwordx4 v[176:177], v[118:121], off offset:256
	s_and_saveexec_b64 s[26:27], s[6:7]
	s_cbranch_execz .LBB0_779
	v_lshl_add_u64 v[118:119], v[152:153], 3, s[2:3]
	s_waitcnt lgkmcnt(1)
	v_add_f32_e32 v113, v113, v114
	s_waitcnt lgkmcnt(0)
	v_add_f32_e32 v114, v115, v116
	global_atomic_add_f32 v[118:119], v113, off
	global_atomic_add_f32 v[118:119], v114, off offset:4

.LBB0_781:
	s_or_b64 exec, exec, s[26:27]
	v_or_b32_e32 v108, 32, v152
	v_ashrrev_i32_e32 v109, 31, v108
	s_waitcnt lgkmcnt(1)
	v_lshlrev_b64 v[96:97], 11, v[108:109]
	v_lshl_add_u64 v[96:97], s[74:75], 0, v[96:97]
	v_lshl_add_u64 v[110:111], v[96:97], 0, v[154:155]
	v_mov_b64_e32 v[114:115], v[192:193]
	v_mov_b64_e32 v[116:117], v[194:195]
	v_mov_b64_e32 v[118:119], v[196:197]
	v_mov_b64_e32 v[120:121], v[198:199]
	v_or_b32_e32 v104, 48, v152
	v_ashrrev_i32_e32 v105, 31, v104
	v_lshlrev_b64 v[96:97], 11, v[104:105]
	v_lshl_add_u64 v[96:97], s[74:75], 0, v[96:97]
	v_lshl_add_u64 v[106:107], v[96:97], 0, v[154:155]
	v_mov_b64_e32 v[100:101], v[200:201]
	v_mov_b64_e32 v[102:103], v[202:203]
	s_waitcnt lgkmcnt(0)
	v_mov_b64_e32 v[96:97], v[204:205]
	v_mov_b64_e32 v[98:99], v[206:207]
	v_add_u32_e32 v224, 0xa0, v152
	v_ashrrev_i32_e32 v225, 31, v224
	v_lshlrev_b64 v[224:225], 11, v[224:225]
	v_lshl_add_u64 v[224:225], s[74:75], 0, v[224:225]
	v_lshl_add_u64 v[224:225], v[224:225], 0, v[154:155]
	global_load_dwordx4 v[192:195], v[224:225], off
	global_load_dwordx4 v[196:199], v[224:225], off offset:256
	v_add_u32_e32 v226, 0xb0, v152
	v_ashrrev_i32_e32 v227, 31, v226
	v_lshlrev_b64 v[226:227], 11, v[226:227]
	v_lshl_add_u64 v[226:227], s[74:75], 0, v[226:227]
	v_lshl_add_u64 v[226:227], v[226:227], 0, v[154:155]
	global_load_dwordx4 v[200:203], v[226:227], off
	global_load_dwordx4 v[204:207], v[226:227], off offset:256
	s_nop 1
	v_lshlrev_b32_e32 v122, 16, v114
	v_and_b32_e32 v123, 0xffff0000, v114
	v_lshlrev_b32_e32 v114, 16, v115
	v_and_b32_e32 v115, 0xffff0000, v115
	v_lshlrev_b32_e32 v124, 16, v116
	v_and_b32_e32 v125, 0xffff0000, v116
	v_lshlrev_b32_e32 v116, 16, v117
	v_and_b32_e32 v117, 0xffff0000, v117
	s_nop 1
	v_lshlrev_b32_e32 v126, 16, v118
	v_and_b32_e32 v127, 0xffff0000, v118
	v_lshlrev_b32_e32 v118, 16, v119
	v_and_b32_e32 v119, 0xffff0000, v119
	v_lshlrev_b32_e32 v128, 16, v120
	v_and_b32_e32 v129, 0xffff0000, v120
	v_lshlrev_b32_e32 v120, 16, v121
	v_and_b32_e32 v121, 0xffff0000, v121
	v_pk_fma_f32 v[94:95], v[114:115], s[16:17], v[94:95] op_sel_hi:[1,0,1]
	v_pk_fma_f32 v[92:93], v[122:123], s[16:17], v[92:93] op_sel_hi:[1,0,1]
	v_pk_fma_f32 v[90:91], v[116:117], s[16:17], v[90:91] op_sel_hi:[1,0,1]
	v_pk_fma_f32 v[88:89], v[124:125], s[16:17], v[88:89] op_sel_hi:[1,0,1]
	v_pk_fma_f32 v[86:87], v[118:119], s[16:17], v[86:87] op_sel_hi:[1,0,1]
	v_pk_fma_f32 v[84:85], v[126:127], s[16:17], v[84:85] op_sel_hi:[1,0,1]
	v_pk_fma_f32 v[114:115], v[120:121], s[16:17], v[82:83] op_sel_hi:[1,0,1]
	v_pk_fma_f32 v[116:117], v[128:129], s[16:17], v[80:81] op_sel_hi:[1,0,1]
	v_cvt_pk_bf16_f32 v80, v92, v93
	v_cvt_pk_bf16_f32 v81, v94, v95
	v_cvt_pk_bf16_f32 v82, v88, v89
	v_add_f32_e32 v83, v92, v93
	v_add_f32_e32 v113, v94, v95
	v_add_f32_e32 v118, v88, v89
	v_add_f32_e32 v119, v90, v91
	v_mul_f32_e32 v93, v93, v93
	v_mul_f32_e32 v95, v95, v95
	v_mul_f32_e32 v89, v89, v89
	v_mul_f32_e32 v120, v91, v91
	v_add_f32_e32 v121, v84, v85
	v_add_f32_e32 v122, v86, v87
	v_add_f32_e32 v123, v116, v117
	v_add_f32_e32 v124, v114, v115
	v_mul_f32_e32 v125, v85, v85
	v_mul_f32_e32 v126, v87, v87
	v_mul_f32_e32 v127, v117, v117
	v_mul_f32_e32 v128, v115, v115
	v_add_f32_e32 v83, v83, v113
	v_add_f32_e32 v113, v118, v119
	v_fmac_f32_e32 v93, v92, v92
	v_fmac_f32_e32 v95, v94, v94
	v_fmac_f32_e32 v89, v88, v88
	v_fmac_f32_e32 v120, v90, v90
	v_add_f32_e32 v88, v121, v122
	v_add_f32_e32 v92, v123, v124
	v_fmac_f32_e32 v125, v84, v84
	v_fmac_f32_e32 v126, v86, v86
	v_fmac_f32_e32 v127, v116, v116
	v_fmac_f32_e32 v128, v114, v114
	v_add_f32_e32 v83, v83, v113
	v_add_f32_e32 v93, v93, v95
	v_add_f32_e32 v89, v89, v120
	v_add_f32_e32 v88, v88, v92
	v_add_f32_e32 v92, v125, v126
	v_add_f32_e32 v94, v127, v128
	v_add_f32_e32 v83, 0, v83
	v_add_f32_e32 v89, v93, v89
	v_add_f32_e32 v92, v92, v94
	v_add_f32_e32 v88, v83, v88
	v_add_f32_e32 v89, v89, v92
	ds_bpermute_b32 v92, v167, v88
	ds_bpermute_b32 v93, v167, v89
	v_cvt_pk_bf16_f32 v83, v90, v91
	global_store_dwordx4 v[110:111], v[80:83], off
	v_cvt_pk_bf16_f32 v84, v84, v85
	v_cvt_pk_bf16_f32 v85, v86, v87
	v_cvt_pk_bf16_f32 v86, v116, v117
	v_cvt_pk_bf16_f32 v87, v114, v115
	global_store_dwordx4 v[110:111], v[84:87], off offset:256
	s_waitcnt lgkmcnt(1)
	v_add_f32_e32 v80, v88, v92
	s_waitcnt lgkmcnt(0)
	v_add_f32_e32 v81, v89, v93
	ds_bpermute_b32 v82, v112, v80
	ds_bpermute_b32 v83, v112, v81
	s_and_saveexec_b64 s[26:27], s[6:7]
	s_cbranch_execz .LBB0_783
	v_lshl_add_u64 v[84:85], v[108:109], 3, s[2:3]
	s_waitcnt lgkmcnt(1)
	v_add_f32_e32 v80, v80, v82
	s_waitcnt lgkmcnt(0)
	v_add_f32_e32 v81, v81, v83
	global_atomic_add_f32 v[84:85], v80, off
	global_atomic_add_f32 v[84:85], v81, off offset:4
.LBB0_783:
	s_or_b64 exec, exec, s[26:27]
	s_nop 1
	v_lshlrev_b32_e32 v80, 16, v100
	v_and_b32_e32 v81, 0xffff0000, v100
	s_waitcnt lgkmcnt(1)
	v_lshlrev_b32_e32 v82, 16, v101
	s_waitcnt lgkmcnt(0)
	v_and_b32_e32 v83, 0xffff0000, v101
	v_pk_fma_f32 v[78:79], v[82:83], s[16:17], v[78:79] op_sel_hi:[1,0,1]
	v_pk_fma_f32 v[76:77], v[80:81], s[16:17], v[76:77] op_sel_hi:[1,0,1]
	v_lshlrev_b32_e32 v80, 16, v102
	v_and_b32_e32 v81, 0xffff0000, v102
	v_lshlrev_b32_e32 v82, 16, v103
	v_and_b32_e32 v83, 0xffff0000, v103
	v_pk_fma_f32 v[74:75], v[82:83], s[16:17], v[74:75] op_sel_hi:[1,0,1]
	v_pk_fma_f32 v[72:73], v[80:81], s[16:17], v[72:73] op_sel_hi:[1,0,1]
	s_nop 1
	v_lshlrev_b32_e32 v80, 16, v96
	v_and_b32_e32 v81, 0xffff0000, v96
	v_lshlrev_b32_e32 v82, 16, v97
	v_and_b32_e32 v83, 0xffff0000, v97
	v_pk_fma_f32 v[70:71], v[82:83], s[16:17], v[70:71] op_sel_hi:[1,0,1]
	v_pk_fma_f32 v[68:69], v[80:81], s[16:17], v[68:69] op_sel_hi:[1,0,1]
	v_lshlrev_b32_e32 v80, 16, v98
	v_and_b32_e32 v81, 0xffff0000, v98
	v_lshlrev_b32_e32 v82, 16, v99
	v_and_b32_e32 v83, 0xffff0000, v99
	v_add_f32_e32 v84, v76, v77
	v_add_f32_e32 v85, v78, v79
	v_pk_fma_f32 v[82:83], v[82:83], s[16:17], v[66:67] op_sel_hi:[1,0,1]
	v_pk_fma_f32 v[80:81], v[80:81], s[16:17], v[64:65] op_sel_hi:[1,0,1]
	v_cvt_pk_bf16_f32 v64, v76, v77
	v_cvt_pk_bf16_f32 v65, v78, v79
	v_cvt_pk_bf16_f32 v66, v72, v73
	v_add_f32_e32 v84, v84, v85
	v_add_f32_e32 v85, v72, v73
	v_mul_f32_e32 v73, v73, v73
	v_fmac_f32_e32 v73, v72, v72
	v_mul_f32_e32 v72, v75, v75
	v_fmac_f32_e32 v72, v74, v74
	v_cvt_pk_bf16_f32 v67, v74, v75
	v_add_f32_e32 v86, v74, v75
	v_add_f32_e32 v72, v73, v72
	v_add_f32_e32 v73, v68, v69
	v_add_f32_e32 v74, v70, v71
	v_mul_f32_e32 v77, v77, v77
	v_add_f32_e32 v73, v73, v74
	v_add_f32_e32 v74, v80, v81
	v_add_f32_e32 v75, v82, v83
	v_fmac_f32_e32 v77, v76, v76
	v_mul_f32_e32 v76, v79, v79
	v_add_f32_e32 v74, v74, v75
	v_fmac_f32_e32 v76, v78, v78
	v_add_f32_e32 v73, v73, v74
	v_mul_f32_e32 v74, v69, v69
	v_mul_f32_e32 v75, v71, v71
	v_add_f32_e32 v76, v77, v76
	v_fmac_f32_e32 v74, v68, v68
	v_fmac_f32_e32 v75, v70, v70
	v_add_f32_e32 v72, v76, v72
	v_add_f32_e32 v74, v74, v75
	v_mul_f32_e32 v75, v81, v81
	v_mul_f32_e32 v76, v83, v83
	v_add_f32_e32 v85, v85, v86
	v_fmac_f32_e32 v75, v80, v80
	v_fmac_f32_e32 v76, v82, v82
	v_add_f32_e32 v84, v84, v85
	v_add_f32_e32 v75, v75, v76
	v_add_f32_e32 v84, 0, v84
	v_add_f32_e32 v74, v74, v75
	v_add_f32_e32 v73, v84, v73
	v_add_f32_e32 v72, v72, v74
	ds_bpermute_b32 v75, v167, v73
	ds_bpermute_b32 v74, v167, v72
	global_store_dwordx4 v[106:107], v[64:67], off
	v_cvt_pk_bf16_f32 v68, v68, v69
	v_cvt_pk_bf16_f32 v69, v70, v71
	v_cvt_pk_bf16_f32 v70, v80, v81
	v_cvt_pk_bf16_f32 v71, v82, v83
	global_store_dwordx4 v[106:107], v[68:71], off offset:256
	s_waitcnt lgkmcnt(1)
	v_add_f32_e32 v64, v73, v75
	s_waitcnt lgkmcnt(0)
	v_add_f32_e32 v66, v72, v74
	ds_bpermute_b32 v65, v112, v64
	ds_bpermute_b32 v67, v112, v66
	s_and_saveexec_b64 s[26:27], s[6:7]
	s_cbranch_execz .LBB0_785
	v_lshl_add_u64 v[68:69], v[104:105], 3, s[2:3]
	s_waitcnt lgkmcnt(1)
	v_add_f32_e32 v64, v64, v65
	s_waitcnt lgkmcnt(0)
	v_add_f32_e32 v65, v66, v67
	global_atomic_add_f32 v[68:69], v64, off
	global_atomic_add_f32 v[68:69], v65, off offset:4
.LBB0_785:
	s_or_b64 exec, exec, s[26:27]
	v_add_u32_e32 v76, 0x80, v152
	v_ashrrev_i32_e32 v77, 31, v76
	s_waitcnt lgkmcnt(1)
	v_lshlrev_b64 v[64:65], 11, v[76:77]
	v_lshl_add_u64 v[64:65], s[74:75], 0, v[64:65]
	v_lshl_add_u64 v[86:87], v[64:65], 0, v[154:155]
	v_mov_b64_e32 v[78:79], v[208:209]
	v_mov_b64_e32 v[80:81], v[210:211]
	v_mov_b64_e32 v[82:83], v[212:213]
	v_mov_b64_e32 v[84:85], v[214:215]
	v_add_u32_e32 v72, 0x90, v152
	v_ashrrev_i32_e32 v73, 31, v72
	v_lshlrev_b64 v[64:65], 11, v[72:73]
	v_lshl_add_u64 v[64:65], s[74:75], 0, v[64:65]
	v_lshl_add_u64 v[74:75], v[64:65], 0, v[154:155]
	v_mov_b64_e32 v[68:69], v[216:217]
	v_mov_b64_e32 v[70:71], v[218:219]
	s_waitcnt lgkmcnt(0)
	v_mov_b64_e32 v[64:65], v[220:221]
	v_mov_b64_e32 v[66:67], v[222:223]
	s_nop 1
	v_lshlrev_b32_e32 v88, 16, v78
	v_and_b32_e32 v89, 0xffff0000, v78
	v_lshlrev_b32_e32 v78, 16, v79
	v_and_b32_e32 v79, 0xffff0000, v79
	v_lshlrev_b32_e32 v90, 16, v80
	v_and_b32_e32 v91, 0xffff0000, v80
	v_lshlrev_b32_e32 v80, 16, v81
	v_and_b32_e32 v81, 0xffff0000, v81
	s_nop 1
	v_lshlrev_b32_e32 v92, 16, v82
	v_and_b32_e32 v93, 0xffff0000, v82
	v_lshlrev_b32_e32 v82, 16, v83
	v_and_b32_e32 v83, 0xffff0000, v83
	v_lshlrev_b32_e32 v94, 16, v84
	v_and_b32_e32 v95, 0xffff0000, v84
	v_lshlrev_b32_e32 v84, 16, v85
	v_and_b32_e32 v85, 0xffff0000, v85
	v_pk_fma_f32 v[62:63], v[78:79], s[16:17], v[62:63] op_sel_hi:[1,0,1]
	v_pk_fma_f32 v[60:61], v[88:89], s[16:17], v[60:61] op_sel_hi:[1,0,1]
	v_pk_fma_f32 v[58:59], v[80:81], s[16:17], v[58:59] op_sel_hi:[1,0,1]
	v_pk_fma_f32 v[56:57], v[90:91], s[16:17], v[56:57] op_sel_hi:[1,0,1]
	v_pk_fma_f32 v[54:55], v[82:83], s[16:17], v[54:55] op_sel_hi:[1,0,1]
	v_pk_fma_f32 v[52:53], v[92:93], s[16:17], v[52:53] op_sel_hi:[1,0,1]
	v_pk_fma_f32 v[78:79], v[84:85], s[16:17], v[50:51] op_sel_hi:[1,0,1]
	v_pk_fma_f32 v[80:81], v[94:95], s[16:17], v[48:49] op_sel_hi:[1,0,1]
	v_cvt_pk_bf16_f32 v48, v60, v61
	v_cvt_pk_bf16_f32 v49, v62, v63
	v_cvt_pk_bf16_f32 v50, v56, v57
	v_add_f32_e32 v51, v60, v61
	v_add_f32_e32 v82, v62, v63
	v_add_f32_e32 v83, v56, v57
	v_add_f32_e32 v84, v58, v59
	v_mul_f32_e32 v61, v61, v61
	v_mul_f32_e32 v63, v63, v63
	v_mul_f32_e32 v57, v57, v57
	v_mul_f32_e32 v85, v59, v59
	v_add_f32_e32 v88, v52, v53
	v_add_f32_e32 v89, v54, v55
	v_add_f32_e32 v90, v80, v81
	v_add_f32_e32 v91, v78, v79
	v_mul_f32_e32 v92, v53, v53
	v_mul_f32_e32 v93, v55, v55
	v_mul_f32_e32 v94, v81, v81
	v_mul_f32_e32 v95, v79, v79
	v_add_f32_e32 v51, v51, v82
	v_add_f32_e32 v82, v83, v84
	v_fmac_f32_e32 v61, v60, v60
	v_fmac_f32_e32 v63, v62, v62
	v_fmac_f32_e32 v57, v56, v56
	v_fmac_f32_e32 v85, v58, v58
	v_add_f32_e32 v56, v88, v89
	v_add_f32_e32 v60, v90, v91
	v_fmac_f32_e32 v92, v52, v52
	v_fmac_f32_e32 v93, v54, v54
	v_fmac_f32_e32 v94, v80, v80
	v_fmac_f32_e32 v95, v78, v78
	v_add_f32_e32 v51, v51, v82
	v_add_f32_e32 v61, v61, v63
	v_add_f32_e32 v57, v57, v85
	v_add_f32_e32 v56, v56, v60
	v_add_f32_e32 v60, v92, v93
	v_add_f32_e32 v62, v94, v95
	v_add_f32_e32 v51, 0, v51
	v_add_f32_e32 v57, v61, v57
	v_add_f32_e32 v60, v60, v62
	v_add_f32_e32 v56, v51, v56
	v_add_f32_e32 v57, v57, v60
	ds_bpermute_b32 v60, v167, v56
	ds_bpermute_b32 v61, v167, v57
	v_cvt_pk_bf16_f32 v51, v58, v59
	global_store_dwordx4 v[86:87], v[48:51], off
	v_cvt_pk_bf16_f32 v52, v52, v53
	v_cvt_pk_bf16_f32 v53, v54, v55
	v_cvt_pk_bf16_f32 v54, v80, v81
	v_cvt_pk_bf16_f32 v55, v78, v79
	global_store_dwordx4 v[86:87], v[52:55], off offset:256
	s_waitcnt lgkmcnt(1)
	v_add_f32_e32 v48, v56, v60
	s_waitcnt lgkmcnt(0)
	v_add_f32_e32 v49, v57, v61
	ds_bpermute_b32 v50, v112, v48
	ds_bpermute_b32 v51, v112, v49
	s_and_saveexec_b64 s[26:27], s[6:7]
	s_cbranch_execz .LBB0_787
	v_lshl_add_u64 v[52:53], v[76:77], 3, s[2:3]
	s_waitcnt lgkmcnt(1)
	v_add_f32_e32 v48, v48, v50
	s_waitcnt lgkmcnt(0)
	v_add_f32_e32 v49, v49, v51
	global_atomic_add_f32 v[52:53], v48, off
	global_atomic_add_f32 v[52:53], v49, off offset:4
.LBB0_787:
	s_or_b64 exec, exec, s[26:27]
	s_nop 1
	v_lshlrev_b32_e32 v48, 16, v68
	v_and_b32_e32 v49, 0xffff0000, v68
	s_waitcnt lgkmcnt(1)
	v_lshlrev_b32_e32 v50, 16, v69
	s_waitcnt lgkmcnt(0)
	v_and_b32_e32 v51, 0xffff0000, v69
	v_pk_fma_f32 v[46:47], v[50:51], s[16:17], v[46:47] op_sel_hi:[1,0,1]
	v_pk_fma_f32 v[44:45], v[48:49], s[16:17], v[44:45] op_sel_hi:[1,0,1]
	v_lshlrev_b32_e32 v48, 16, v70
	v_and_b32_e32 v49, 0xffff0000, v70
	v_lshlrev_b32_e32 v50, 16, v71
	v_and_b32_e32 v51, 0xffff0000, v71
	v_pk_fma_f32 v[42:43], v[50:51], s[16:17], v[42:43] op_sel_hi:[1,0,1]
	v_pk_fma_f32 v[40:41], v[48:49], s[16:17], v[40:41] op_sel_hi:[1,0,1]
	s_nop 1
	v_lshlrev_b32_e32 v48, 16, v64
	v_and_b32_e32 v49, 0xffff0000, v64
	v_lshlrev_b32_e32 v50, 16, v65
	v_and_b32_e32 v51, 0xffff0000, v65
	v_pk_fma_f32 v[38:39], v[50:51], s[16:17], v[38:39] op_sel_hi:[1,0,1]
	v_pk_fma_f32 v[36:37], v[48:49], s[16:17], v[36:37] op_sel_hi:[1,0,1]
	v_lshlrev_b32_e32 v48, 16, v66
	v_and_b32_e32 v49, 0xffff0000, v66
	v_lshlrev_b32_e32 v50, 16, v67
	v_and_b32_e32 v51, 0xffff0000, v67
	v_add_f32_e32 v52, v44, v45
	v_add_f32_e32 v53, v46, v47
	v_pk_fma_f32 v[50:51], v[50:51], s[16:17], v[34:35] op_sel_hi:[1,0,1]
	v_pk_fma_f32 v[48:49], v[48:49], s[16:17], v[32:33] op_sel_hi:[1,0,1]
	v_cvt_pk_bf16_f32 v32, v44, v45
	v_cvt_pk_bf16_f32 v33, v46, v47
	v_cvt_pk_bf16_f32 v34, v40, v41
	v_add_f32_e32 v52, v52, v53
	v_add_f32_e32 v53, v40, v41
	v_mul_f32_e32 v41, v41, v41
	v_fmac_f32_e32 v41, v40, v40
	v_mul_f32_e32 v40, v43, v43
	v_fmac_f32_e32 v40, v42, v42
	v_cvt_pk_bf16_f32 v35, v42, v43
	v_add_f32_e32 v54, v42, v43
	v_add_f32_e32 v40, v41, v40
	v_add_f32_e32 v41, v36, v37
	v_add_f32_e32 v42, v38, v39
	v_mul_f32_e32 v45, v45, v45
	v_add_f32_e32 v41, v41, v42
	v_add_f32_e32 v42, v48, v49
	v_add_f32_e32 v43, v50, v51
	v_fmac_f32_e32 v45, v44, v44
	v_mul_f32_e32 v44, v47, v47
	v_add_f32_e32 v42, v42, v43
	v_fmac_f32_e32 v44, v46, v46
	v_add_f32_e32 v41, v41, v42
	v_mul_f32_e32 v42, v37, v37
	v_mul_f32_e32 v43, v39, v39
	v_add_f32_e32 v44, v45, v44
	v_fmac_f32_e32 v42, v36, v36
	v_fmac_f32_e32 v43, v38, v38
	v_add_f32_e32 v40, v44, v40
	v_add_f32_e32 v42, v42, v43
	v_mul_f32_e32 v43, v49, v49
	v_mul_f32_e32 v44, v51, v51
	v_add_f32_e32 v53, v53, v54
	v_fmac_f32_e32 v43, v48, v48
	v_fmac_f32_e32 v44, v50, v50
	v_add_f32_e32 v52, v52, v53
	v_add_f32_e32 v43, v43, v44
	v_add_f32_e32 v52, 0, v52
	v_add_f32_e32 v42, v42, v43
	v_add_f32_e32 v41, v52, v41
	v_add_f32_e32 v40, v40, v42
	ds_bpermute_b32 v43, v167, v41
	ds_bpermute_b32 v42, v167, v40
	global_store_dwordx4 v[74:75], v[32:35], off
	v_cvt_pk_bf16_f32 v36, v36, v37
	v_cvt_pk_bf16_f32 v37, v38, v39
	v_cvt_pk_bf16_f32 v38, v48, v49
	v_cvt_pk_bf16_f32 v39, v50, v51
	global_store_dwordx4 v[74:75], v[36:39], off offset:256
	s_waitcnt lgkmcnt(1)
	v_add_f32_e32 v32, v41, v43
	s_waitcnt lgkmcnt(0)
	v_add_f32_e32 v34, v40, v42
	ds_bpermute_b32 v33, v112, v32
	ds_bpermute_b32 v35, v112, v34
	s_and_saveexec_b64 s[26:27], s[6:7]
	s_cbranch_execz .LBB0_789
	v_lshl_add_u64 v[36:37], v[72:73], 3, s[2:3]
	s_waitcnt lgkmcnt(1)
	v_add_f32_e32 v32, v32, v33
	s_waitcnt lgkmcnt(0)
	v_add_f32_e32 v33, v34, v35
	global_atomic_add_f32 v[36:37], v32, off
	global_atomic_add_f32 v[36:37], v33, off offset:4
.LBB0_789:
	s_or_b64 exec, exec, s[26:27]
	v_add_u32_e32 v44, 0xa0, v152
	v_ashrrev_i32_e32 v45, 31, v44
	s_waitcnt lgkmcnt(1)
	v_lshlrev_b64 v[32:33], 11, v[44:45]
	v_lshl_add_u64 v[32:33], s[74:75], 0, v[32:33]
	v_lshl_add_u64 v[54:55], v[32:33], 0, v[154:155]
	s_waitcnt vmcnt(8)
	v_mov_b64_e32 v[46:47], v[192:193]
	v_mov_b64_e32 v[48:49], v[194:195]
	v_mov_b64_e32 v[50:51], v[196:197]
	v_mov_b64_e32 v[52:53], v[198:199]
	v_add_u32_e32 v40, 0xb0, v152
	v_ashrrev_i32_e32 v41, 31, v40
	v_lshlrev_b64 v[32:33], 11, v[40:41]
	v_lshl_add_u64 v[32:33], s[74:75], 0, v[32:33]
	v_lshl_add_u64 v[42:43], v[32:33], 0, v[154:155]
	v_mov_b64_e32 v[36:37], v[200:201]
	v_mov_b64_e32 v[38:39], v[202:203]
	s_waitcnt lgkmcnt(0)
	v_mov_b64_e32 v[32:33], v[204:205]
	v_mov_b64_e32 v[34:35], v[206:207]
	s_nop 1
	v_lshlrev_b32_e32 v56, 16, v46
	v_and_b32_e32 v57, 0xffff0000, v46
	v_lshlrev_b32_e32 v46, 16, v47
	v_and_b32_e32 v47, 0xffff0000, v47
	v_lshlrev_b32_e32 v58, 16, v48
	v_and_b32_e32 v59, 0xffff0000, v48
	v_lshlrev_b32_e32 v48, 16, v49
	v_and_b32_e32 v49, 0xffff0000, v49
	s_nop 1
	v_lshlrev_b32_e32 v60, 16, v50
	v_and_b32_e32 v61, 0xffff0000, v50
	v_lshlrev_b32_e32 v50, 16, v51
	v_and_b32_e32 v51, 0xffff0000, v51
	v_lshlrev_b32_e32 v62, 16, v52
	v_and_b32_e32 v63, 0xffff0000, v52
	v_lshlrev_b32_e32 v52, 16, v53
	v_and_b32_e32 v53, 0xffff0000, v53
	v_pk_fma_f32 v[30:31], v[46:47], s[16:17], v[30:31] op_sel_hi:[1,0,1]
	v_pk_fma_f32 v[28:29], v[56:57], s[16:17], v[28:29] op_sel_hi:[1,0,1]
	v_pk_fma_f32 v[26:27], v[48:49], s[16:17], v[26:27] op_sel_hi:[1,0,1]
	v_pk_fma_f32 v[24:25], v[58:59], s[16:17], v[24:25] op_sel_hi:[1,0,1]
	v_pk_fma_f32 v[22:23], v[50:51], s[16:17], v[22:23] op_sel_hi:[1,0,1]
	v_pk_fma_f32 v[20:21], v[60:61], s[16:17], v[20:21] op_sel_hi:[1,0,1]
	v_pk_fma_f32 v[46:47], v[52:53], s[16:17], v[18:19] op_sel_hi:[1,0,1]
	v_pk_fma_f32 v[48:49], v[62:63], s[16:17], v[16:17] op_sel_hi:[1,0,1]
	v_cvt_pk_bf16_f32 v16, v28, v29
	v_cvt_pk_bf16_f32 v17, v30, v31
	v_cvt_pk_bf16_f32 v18, v24, v25
	v_add_f32_e32 v19, v28, v29
	v_add_f32_e32 v50, v30, v31
	v_add_f32_e32 v51, v24, v25
	v_add_f32_e32 v52, v26, v27
	v_mul_f32_e32 v29, v29, v29
	v_mul_f32_e32 v31, v31, v31
	v_mul_f32_e32 v25, v25, v25
	v_mul_f32_e32 v53, v27, v27
	v_add_f32_e32 v56, v20, v21
	v_add_f32_e32 v57, v22, v23
	v_add_f32_e32 v58, v48, v49
	v_add_f32_e32 v59, v46, v47
	v_mul_f32_e32 v60, v21, v21
	v_mul_f32_e32 v61, v23, v23
	v_mul_f32_e32 v62, v49, v49
	v_mul_f32_e32 v63, v47, v47
	v_add_f32_e32 v19, v19, v50
	v_add_f32_e32 v50, v51, v52
	v_fmac_f32_e32 v29, v28, v28
	v_fmac_f32_e32 v31, v30, v30
	v_fmac_f32_e32 v25, v24, v24
	v_fmac_f32_e32 v53, v26, v26
	v_add_f32_e32 v24, v56, v57
	v_add_f32_e32 v28, v58, v59
	v_fmac_f32_e32 v60, v20, v20
	v_fmac_f32_e32 v61, v22, v22
	v_fmac_f32_e32 v62, v48, v48
	v_fmac_f32_e32 v63, v46, v46
	v_add_f32_e32 v19, v19, v50
	v_add_f32_e32 v29, v29, v31
	v_add_f32_e32 v25, v25, v53
	v_add_f32_e32 v24, v24, v28
	v_add_f32_e32 v28, v60, v61
	v_add_f32_e32 v30, v62, v63
	v_add_f32_e32 v19, 0, v19
	v_add_f32_e32 v25, v29, v25
	v_add_f32_e32 v28, v28, v30
	v_add_f32_e32 v24, v19, v24
	v_add_f32_e32 v25, v25, v28
	ds_bpermute_b32 v28, v167, v24
	ds_bpermute_b32 v29, v167, v25
	v_cvt_pk_bf16_f32 v19, v26, v27
	global_store_dwordx4 v[54:55], v[16:19], off
	v_cvt_pk_bf16_f32 v20, v20, v21
	v_cvt_pk_bf16_f32 v21, v22, v23
	v_cvt_pk_bf16_f32 v22, v48, v49
	v_cvt_pk_bf16_f32 v23, v46, v47
	global_store_dwordx4 v[54:55], v[20:23], off offset:256
	s_waitcnt lgkmcnt(1)
	v_add_f32_e32 v16, v24, v28
	s_waitcnt lgkmcnt(0)
	v_add_f32_e32 v17, v25, v29
	ds_bpermute_b32 v18, v112, v16
	ds_bpermute_b32 v19, v112, v17
	s_and_saveexec_b64 s[26:27], s[6:7]
	s_cbranch_execz .LBB0_791
	v_lshl_add_u64 v[20:21], v[44:45], 3, s[2:3]
	s_waitcnt lgkmcnt(1)
	v_add_f32_e32 v16, v16, v18
	s_waitcnt lgkmcnt(0)
	v_add_f32_e32 v17, v17, v19
	global_atomic_add_f32 v[20:21], v16, off
	global_atomic_add_f32 v[20:21], v17, off offset:4
.LBB0_791:
	s_or_b64 exec, exec, s[26:27]
	s_nop 1
	v_lshlrev_b32_e32 v16, 16, v36
	v_and_b32_e32 v17, 0xffff0000, v36
	s_waitcnt lgkmcnt(1)
	v_lshlrev_b32_e32 v18, 16, v37
	s_waitcnt lgkmcnt(0)
	v_and_b32_e32 v19, 0xffff0000, v37
	v_pk_fma_f32 v[14:15], v[18:19], s[16:17], v[14:15] op_sel_hi:[1,0,1]
	v_pk_fma_f32 v[12:13], v[16:17], s[16:17], v[12:13] op_sel_hi:[1,0,1]
	v_lshlrev_b32_e32 v16, 16, v38
	v_and_b32_e32 v17, 0xffff0000, v38
	v_lshlrev_b32_e32 v18, 16, v39
	v_and_b32_e32 v19, 0xffff0000, v39
	v_pk_fma_f32 v[10:11], v[18:19], s[16:17], v[10:11] op_sel_hi:[1,0,1]
	v_pk_fma_f32 v[8:9], v[16:17], s[16:17], v[8:9] op_sel_hi:[1,0,1]
	s_nop 1
	v_lshlrev_b32_e32 v16, 16, v32
	v_and_b32_e32 v17, 0xffff0000, v32
	v_lshlrev_b32_e32 v18, 16, v33
	v_and_b32_e32 v19, 0xffff0000, v33
	v_pk_fma_f32 v[6:7], v[18:19], s[16:17], v[6:7] op_sel_hi:[1,0,1]
	v_pk_fma_f32 v[4:5], v[16:17], s[16:17], v[4:5] op_sel_hi:[1,0,1]
	v_lshlrev_b32_e32 v16, 16, v34
	v_and_b32_e32 v17, 0xffff0000, v34
	v_lshlrev_b32_e32 v18, 16, v35
	v_and_b32_e32 v19, 0xffff0000, v35
	v_add_f32_e32 v20, v12, v13
	v_add_f32_e32 v21, v14, v15
	v_pk_fma_f32 v[18:19], v[18:19], s[16:17], v[2:3] op_sel_hi:[1,0,1]
	v_pk_fma_f32 v[16:17], v[16:17], s[16:17], v[0:1] op_sel_hi:[1,0,1]
	v_cvt_pk_bf16_f32 v0, v12, v13
	v_cvt_pk_bf16_f32 v1, v14, v15
	v_cvt_pk_bf16_f32 v2, v8, v9
	v_add_f32_e32 v20, v20, v21
	v_add_f32_e32 v21, v8, v9
	v_mul_f32_e32 v9, v9, v9
	v_fmac_f32_e32 v9, v8, v8
	v_mul_f32_e32 v8, v11, v11
	v_fmac_f32_e32 v8, v10, v10
	v_cvt_pk_bf16_f32 v3, v10, v11
	v_add_f32_e32 v22, v10, v11
	v_add_f32_e32 v8, v9, v8
	v_add_f32_e32 v9, v4, v5
	v_add_f32_e32 v10, v6, v7
	v_mul_f32_e32 v13, v13, v13
	v_add_f32_e32 v9, v9, v10
	v_add_f32_e32 v10, v16, v17
	v_add_f32_e32 v11, v18, v19
	v_fmac_f32_e32 v13, v12, v12
	v_mul_f32_e32 v12, v15, v15
	v_add_f32_e32 v10, v10, v11
	v_fmac_f32_e32 v12, v14, v14
	v_add_f32_e32 v9, v9, v10
	v_mul_f32_e32 v10, v5, v5
	v_mul_f32_e32 v11, v7, v7
	v_add_f32_e32 v12, v13, v12
	v_fmac_f32_e32 v10, v4, v4
	v_fmac_f32_e32 v11, v6, v6
	v_add_f32_e32 v8, v12, v8
	v_add_f32_e32 v10, v10, v11
	v_mul_f32_e32 v11, v17, v17
	v_mul_f32_e32 v12, v19, v19
	v_add_f32_e32 v21, v21, v22
	v_fmac_f32_e32 v11, v16, v16
	v_fmac_f32_e32 v12, v18, v18
	v_add_f32_e32 v20, v20, v21
	v_add_f32_e32 v11, v11, v12
	v_add_f32_e32 v20, 0, v20
	v_add_f32_e32 v10, v10, v11
	v_add_f32_e32 v9, v20, v9
	v_add_f32_e32 v8, v8, v10
	ds_bpermute_b32 v11, v167, v9
	ds_bpermute_b32 v10, v167, v8
	global_store_dwordx4 v[42:43], v[0:3], off
	v_cvt_pk_bf16_f32 v4, v4, v5
	v_cvt_pk_bf16_f32 v5, v6, v7
	v_cvt_pk_bf16_f32 v6, v16, v17
	v_cvt_pk_bf16_f32 v7, v18, v19
	global_store_dwordx4 v[42:43], v[4:7], off offset:256
	s_waitcnt lgkmcnt(1)
	v_add_f32_e32 v0, v9, v11
	s_waitcnt lgkmcnt(0)
	v_add_f32_e32 v2, v8, v10
	ds_bpermute_b32 v1, v112, v0
	ds_bpermute_b32 v3, v112, v2
	s_and_saveexec_b64 s[26:27], s[6:7]
	s_cbranch_execz .LBB0_793
	v_lshl_add_u64 v[4:5], v[40:41], 3, s[2:3]
	s_waitcnt lgkmcnt(1)
	v_add_f32_e32 v0, v0, v1
	s_waitcnt lgkmcnt(0)
	v_add_f32_e32 v1, v2, v3
	global_atomic_add_f32 v[4:5], v0, off
	global_atomic_add_f32 v[4:5], v1, off offset:4
